# attention epilogue dwordx4 stores (T21) with the loop back-edge counted waits recounted for 4 stores (vmcnt 11..8 -> 7..4)
# baseline (speedup 1.0000x reference)
; __device__ __forceinline__ void attn_phase_mfma(const Ctx& c, unsigned char* lds_raw, bool do_store) {
;     ...
;         const int un = u + G;
;         if (un < NAT) ATT_PREFETCH(un);
;     ...
;         __syncthreads();
;         if (un >= NAT) break;
;         u = un;
;     }
.LBB0_358:
	s_or_b64 exec, exec, s[0:1]
	s_add_i32 s4, s4, s5
	s_waitcnt vmcnt(7)
	v_mov_b64_e32 v[10:11], v[142:143]
	s_waitcnt vmcnt(6)
	v_mov_b64_e32 v[2:3], v[138:139]
	s_waitcnt vmcnt(5)
	v_mov_b64_e32 v[14:15], v[134:135]
	s_waitcnt vmcnt(4)
	v_mov_b64_e32 v[6:7], v[130:131]
	s_cmpk_lt_i32 s33, 0x600
	v_mov_b64_e32 v[12:13], v[144:145]
	v_mov_b64_e32 v[4:5], v[140:141]
	v_mov_b64_e32 v[16:17], v[136:137]
	v_mov_b64_e32 v[8:9], v[132:133]
	s_barrier
	s_cbranch_scc0 .LBB0_381
